# MoBA attention too: K/V tiles staged once per workgroup in LDS by DMA (3-stage ring), fragments read from LDS
# speedup vs baseline: 1.0299x; 1.0094x over previous
; #define MFMA32(a, b, c) __builtin_amdgcn_mfma_f32_32x32x16_bf16((a), (b), (c), 0, 0, 0)
; template <class KP, class VP, class ACT, class FILL>
; DI void attn_loop(AttnSt& st, const bf16x8 (&qf)[4], int k0, int k1, size_t vstride, KP kp, VP vp, ACT act, FILL fill) {
;   KVT cur, nxt;
;   {
;     KVT t0; load_kv(t0, kp(k0), vp(k0), vstride);
; #pragma unroll
;     for (int i = 0; i < 8; ++i) cur.v[i] = t0.v[i];
; #pragma unroll
;     for (int i = 0; i < 4; ++i) cur.k[i] = t0.k[i];
;   }
;   f32x16 s_cur;
;   { const float z = 0.f;
; #pragma unroll
;     for (int i = 0; i < 16; ++i) s_cur[i] = z; }
; #pragma unroll
;   for (int ss = 0; ss < 4; ++ss) s_cur = MFMA32(cur.k[ss], qf[ss], s_cur);
;   {
;     const int kn = (k0 < k1) ? k0 + 1 : k1;
;     const bf16_t* krow = kp(kn);
; #pragma unroll
;     for (int ss = 0; ss < 4; ++ss) nxt.k[ss] = *(const bf16x8*)(krow + 512 * ss);
;   }
; DI void moba_item(const Params& p, int b, int hd, int qb, const unsigned char* blut, const float* tbl) {
;     ...
;   mmask |= 1u << c;
;   const bf16_t* K = (const bf16_t*)(p.ws + OFF_KM) + (size_t)bh * 4096 * 64;
;   const bf16_t* Vt = (const bf16_t*)(p.ws + OFF_VMT) + (size_t)bh * 64 * 4096;
;   AttnSt st; attn_init(st);
;   attn_loop(st, qf, 0, qb, 32,
.LBB0_942:
	s_andn2_saveexec_b64 s[8:9], s[8:9]
	v_mov_b32_e32 v0, 0
	s_or_b64 exec, exec, s[8:9]
	v_readlane_b32 s8, v253, 49
	v_lshlrev_b32_e32 v1, 3, v18
	v_lshlrev_b64 v[14:15], 19, v[16:17]
	v_readlane_b32 s9, v253, 50
	v_lshl_or_b32 v130, v19, 8, v1
	v_lshlrev_b32_e32 v26, 1, v130
	v_lshl_add_u64 v[16:17], s[8:9], 0, v[14:15]
	v_mov_b32_e32 v27, v131
	v_lshl_add_u64 v[134:135], v[16:17], 0, v[26:27]
	global_load_dwordx4 v[2:5], v[134:135], off
	global_load_dwordx4 v[6:9], v[134:135], off offset:1024
	global_load_dwordx4 v[10:13], v[134:135], off offset:2048
	global_load_dwordx4 v[22:25], v[134:135], off offset:3072
	v_readlane_b32 s8, v253, 51
	v_cmp_eq_u32_e32 vcc, 0, v154
	v_readlane_b32 s9, v253, 52
	v_mov_b32_e32 v29, v131
	v_cndmask_b32_e64 v28, v197, 0, vcc
	v_lshl_add_u64 v[14:15], s[8:9], 0, v[14:15]
	v_lshl_add_u64 v[16:17], v[16:17], 0, v[28:29]
	v_lshl_add_u64 v[16:17], v[16:17], 0, v[26:27]
	v_lshl_add_u64 v[136:137], v[14:15], 0, v[130:131]
	global_load_dwordx4 v[108:111], v[16:17], off offset:3072
	global_load_dwordx4 v[104:107], v[16:17], off offset:2048
	global_load_dwordx4 v[100:103], v[16:17], off offset:1024
	global_load_dwordx4 v[96:99], v[16:17], off
	global_load_dwordx2 v[114:115], v[136:137], off offset:3584
	global_load_dwordx2 v[112:113], v[136:137], off offset:3072
	global_load_dwordx2 v[118:119], v[136:137], off offset:2560
	global_load_dwordx2 v[116:117], v[136:137], off offset:2048
	global_load_dwordx2 v[122:123], v[136:137], off offset:1536
	global_load_dwordx2 v[120:121], v[136:137], off offset:1024
	global_load_dwordx2 v[126:127], v[136:137], off offset:512
	global_load_dwordx2 v[124:125], v[136:137], off
	s_mov_b32 s56, 0
	v_lshrrev_b32_e32 v1, 3, v154
	s_mov_b32 s57, s56
	v_lshl_or_b32 v157, 1, v1, v0
	s_mov_b32 s58, s56
	s_mov_b32 s59, s56
	s_mov_b32 s60, s56
	s_mov_b32 s61, s56
	s_mov_b32 s62, s56
	s_mov_b32 s63, s56
	s_mov_b32 s64, s56
	s_mov_b32 s65, s56
	s_mov_b32 s66, s56
	s_mov_b32 s67, s56
	s_mov_b32 s68, s56
	s_mov_b32 s69, s56
	s_mov_b32 s70, s56
	s_mov_b32 s71, s56
	v_sub_u32_e32 v16, 0, v21
	v_lshlrev_b32_e32 v155, 2, v19
	v_lshlrev_b32_e32 v133, 6, v20
	v_lshl_add_u32 v156, v20, 7, 0
	v_sub_u32_e32 v158, v18, v155
	v_lshl_add_u32 v159, v16, 5, v208
	v_mov_b32_e32 v160, 0
	v_mov_b32_e32 v161, 0xff800000
	s_waitcnt vmcnt(15)
	v_mfma_f32_32x32x16_bf16 v[48:63], v[2:5], v[80:83], 0
	s_waitcnt vmcnt(14)
	v_mfma_f32_32x32x16_bf16 v[48:63], v[6:9], v[84:87], v[48:63]
	s_waitcnt vmcnt(13)
	v_mfma_f32_32x32x16_bf16 v[48:63], v[10:13], v[88:91], v[48:63]
	v_mov_b64_e32 v[0:1], s[56:57]
	v_mov_b64_e32 v[14:15], s[70:71]
	v_mov_b64_e32 v[2:3], s[58:59]
	v_mov_b64_e32 v[4:5], s[60:61]
	v_mov_b64_e32 v[6:7], s[62:63]
	v_mov_b64_e32 v[8:9], s[64:65]
	v_mov_b64_e32 v[10:11], s[66:67]
	s_waitcnt vmcnt(12)
	v_mfma_f32_32x32x16_bf16 v[48:63], v[22:25], v[92:95], v[48:63]
	v_mov_b64_e32 v[12:13], s[68:69]
	v_mov_b64_e32 v[30:31], v[14:15]
	s_mov_b64 s[58:59], 0
	v_mov_b64_e32 v[28:29], v[12:13]
	v_mov_b64_e32 v[26:27], v[10:11]
	v_mov_b64_e32 v[24:25], v[8:9]
	v_mov_b64_e32 v[22:23], v[6:7]
	v_mov_b64_e32 v[20:21], v[4:5]
	v_mov_b64_e32 v[18:19], v[2:3]
	v_mov_b64_e32 v[16:17], v[0:1]
	s_waitcnt vmcnt(0)
	v_readfirstlane_b32 s60, v154
	v_lshrrev_b32_e32 v184, 6, v129
	v_and_b32_e32 v185, 63, v129
	v_lshlrev_b32_e32 v185, 3, v185
	v_readfirstlane_b32 s58, v184
	v_mov_b32_e32 v162, s60
	v_mov_b32_e32 v163, 0x1940
	v_lshl_add_u32 v172, v184, 2, v163
	ds_write_b32 v172, v162
	s_waitcnt lgkmcnt(0)
	s_barrier
	ds_read_b128 v[164:167], v163
	ds_read_b128 v[168:171], v163 offset:16
	s_waitcnt lgkmcnt(0)
	v_max3_u32 v164, v164, v165, v166
	v_max3_u32 v164, v164, v167, v168
	v_max3_u32 v164, v164, v169, v170
	v_max_u32_e32 v164, v164, v171
	s_nop 0
	v_readfirstlane_b32 s59, v164
	s_mov_b32 s56, 0
	s_mov_b32 s23, 0
	s_mov_b32 s100, 0x10000
	s_lshr_b32 s24, s59, 1
	s_min_u32 s24, s23, s24
	s_lshl_b32 s26, s24, 13
	s_lshl_b32 s24, s58, 10
	s_add_u32 s26, s26, s24
	s_mov_b32 s27, 0
	v_lshl_add_u64 v[186:187], v[134:135], 0, s[26:27]
	v_lshl_add_u64 v[218:219], v[136:137], 0, s[26:27]
	v_add_co_u32_e32 v218, vcc, v218, v185
	v_addc_co_u32_e32 v219, vcc, 0, v219, vcc
	s_add_u32 s24, s24, s100
	s_mov_b32 m0, s24
	s_nop 0
	global_load_lds_dwordx4 v[186:187], off
	s_add_u32 s24, s24, 0x2000
	s_mov_b32 m0, s24
	s_nop 0
	global_load_lds_dwordx4 v[218:219], off
	s_mov_b32 s23, 1
	s_mov_b32 s100, 0x14000
	s_lshr_b32 s24, s59, 1
	s_min_u32 s24, s23, s24
	s_lshl_b32 s26, s24, 13
	s_lshl_b32 s24, s58, 10
	s_add_u32 s26, s26, s24
	s_mov_b32 s27, 0
	v_lshl_add_u64 v[186:187], v[134:135], 0, s[26:27]
	v_lshl_add_u64 v[218:219], v[136:137], 0, s[26:27]
	v_add_co_u32_e32 v218, vcc, v218, v185
	v_addc_co_u32_e32 v219, vcc, 0, v219, vcc
	s_add_u32 s24, s24, s100
	s_mov_b32 m0, s24
	s_nop 0
	global_load_lds_dwordx4 v[186:187], off
	s_add_u32 s24, s24, 0x2000
	s_mov_b32 m0, s24
	s_nop 0
	global_load_lds_dwordx4 v[218:219], off
	s_mov_b32 s100, 0x10000
	v_lshrrev_b32_e32 v184, 6, v129
	v_mul_u32_u24_e32 v184, 6912, v184
	v_add_u32_e32 v180, 8192, v184
	v_and_b32_e32 v184, 63, v129
	v_add_u32_e32 v162, -64, v184
	v_mov_b32_e32 v162, 0
	v_mov_b32_e32 v163, v184
	v_add_u32_e32 v164, 64, v184
	v_add_u32_e32 v165, 128, v184
	v_add_u32_e32 v166, 192, v184
	v_add_u32_e32 v167, 256, v184
	v_add_u32_e32 v168, 320, v184
	v_add_u32_e32 v169, 384, v184
	v_add_u32_e32 v170, 448, v184
	ds_read_u8 v162, v162
	ds_read_u8 v163, v163
	ds_read_u8 v164, v164
	ds_read_u8 v165, v165
	ds_read_u8 v166, v166
	ds_read_u8 v167, v167
	ds_read_u8 v168, v168
	ds_read_u8 v169, v169
	ds_read_u8 v170, v170
	s_waitcnt lgkmcnt(8)
	v_lshl_add_u32 v162, v162, 2, v156
	s_waitcnt lgkmcnt(7)
; DI void bias16(const unsigned char* blut, const float* tblh, const int (&dist)[16], float (&bv)[16]) {
;   int bk[16];
; #pragma unroll
;   for (int i = 0; i < 16; ++i) { const int d = dist[i] < 0 ? 0 : (dist[i] > 2048 ? 2048 : dist[i]); bk[i] = blut[d]; }
; #pragma unroll
;   for (int i = 0; i < 16; ++i) asm volatile("" : "+v"(bk[i]));
; #pragma unroll
;   for (int i = 0; i < 16; ++i) bv[i] = tblh[bk[i]];
; #pragma unroll
;   for (int i = 0; i < 16; ++i) asm volatile("" : "+v"(bv[i]));
; }
	v_lshl_add_u32 v163, v163, 2, v156
	s_waitcnt lgkmcnt(6)
	v_lshl_add_u32 v164, v164, 2, v156
	s_waitcnt lgkmcnt(5)
	v_lshl_add_u32 v165, v165, 2, v156
	s_waitcnt lgkmcnt(4)
	v_lshl_add_u32 v166, v166, 2, v156
	s_waitcnt lgkmcnt(3)
	v_lshl_add_u32 v167, v167, 2, v156
	s_waitcnt lgkmcnt(2)
	v_lshl_add_u32 v168, v168, 2, v156
	s_waitcnt lgkmcnt(1)
	v_lshl_add_u32 v169, v169, 2, v156
	s_waitcnt lgkmcnt(0)
	v_lshl_add_u32 v170, v170, 2, v156
	ds_read_b32 v162, v162 offset:4864
	ds_read_b32 v163, v163 offset:4864
	ds_read_b32 v164, v164 offset:4864
	ds_read_b32 v165, v165 offset:4864
	ds_read_b32 v166, v166 offset:4864
	ds_read_b32 v167, v167 offset:4864
	ds_read_b32 v168, v168 offset:4864
	ds_read_b32 v169, v169 offset:4864
	ds_read_b32 v170, v170 offset:4864
	v_lshl_add_u32 v182, v184, 2, v180
	s_waitcnt lgkmcnt(8)
	ds_write_b32 v182, v162 offset:0
	s_waitcnt lgkmcnt(7)
	ds_write_b32 v182, v163 offset:256
	s_waitcnt lgkmcnt(6)
	ds_write_b32 v182, v164 offset:512
	s_waitcnt lgkmcnt(5)
	ds_write_b32 v182, v165 offset:768
	s_waitcnt lgkmcnt(4)
	ds_write_b32 v182, v166 offset:1024
	s_waitcnt lgkmcnt(3)
	ds_write_b32 v182, v167 offset:1280
	s_waitcnt lgkmcnt(2)
	ds_write_b32 v182, v168 offset:1536
	s_waitcnt lgkmcnt(1)
	ds_write_b32 v182, v169 offset:1792
	s_waitcnt lgkmcnt(0)
	ds_write_b32 v182, v170 offset:2048
	v_add_u32_e32 v162, 512, v184
	v_add_u32_e32 v163, 576, v184
	v_add_u32_e32 v164, 640, v184
	v_add_u32_e32 v165, 704, v184
	v_add_u32_e32 v166, 768, v184
	v_add_u32_e32 v167, 832, v184
	v_add_u32_e32 v168, 896, v184
	v_add_u32_e32 v169, 960, v184
	v_add_u32_e32 v170, 1024, v184
	ds_read_u8 v162, v162
	ds_read_u8 v163, v163
	ds_read_u8 v164, v164
	ds_read_u8 v165, v165
	ds_read_u8 v166, v166
	ds_read_u8 v167, v167
	ds_read_u8 v168, v168
	ds_read_u8 v169, v169
	ds_read_u8 v170, v170
	s_waitcnt lgkmcnt(8)
	v_lshl_add_u32 v162, v162, 2, v156
	s_waitcnt lgkmcnt(7)
	v_lshl_add_u32 v163, v163, 2, v156
	s_waitcnt lgkmcnt(6)
	v_lshl_add_u32 v164, v164, 2, v156
	s_waitcnt lgkmcnt(5)
	v_lshl_add_u32 v165, v165, 2, v156
	s_waitcnt lgkmcnt(4)
	v_lshl_add_u32 v166, v166, 2, v156
	s_waitcnt lgkmcnt(3)
	v_lshl_add_u32 v167, v167, 2, v156
	s_waitcnt lgkmcnt(2)
	v_lshl_add_u32 v168, v168, 2, v156
	s_waitcnt lgkmcnt(1)
	v_lshl_add_u32 v169, v169, 2, v156
	s_waitcnt lgkmcnt(0)
	v_lshl_add_u32 v170, v170, 2, v156
	ds_read_b32 v162, v162 offset:4864
	ds_read_b32 v163, v163 offset:4864
	ds_read_b32 v164, v164 offset:4864
	ds_read_b32 v165, v165 offset:4864
	ds_read_b32 v166, v166 offset:4864
	ds_read_b32 v167, v167 offset:4864
	ds_read_b32 v168, v168 offset:4864
	ds_read_b32 v169, v169 offset:4864
	ds_read_b32 v170, v170 offset:4864
	v_lshl_add_u32 v182, v184, 2, v180
	s_waitcnt lgkmcnt(8)
	ds_write_b32 v182, v162 offset:2304
	s_waitcnt lgkmcnt(7)
	ds_write_b32 v182, v163 offset:2560
	s_waitcnt lgkmcnt(6)
	ds_write_b32 v182, v164 offset:2816
	s_waitcnt lgkmcnt(5)
	ds_write_b32 v182, v165 offset:3072
	s_waitcnt lgkmcnt(4)
	ds_write_b32 v182, v166 offset:3328
	s_waitcnt lgkmcnt(3)
	ds_write_b32 v182, v167 offset:3584
	s_waitcnt lgkmcnt(2)
	ds_write_b32 v182, v168 offset:3840
	s_waitcnt lgkmcnt(1)
	ds_write_b32 v182, v169 offset:4096
	s_waitcnt lgkmcnt(0)
	ds_write_b32 v182, v170 offset:4352
	v_add_u32_e32 v162, 1088, v184
	v_add_u32_e32 v163, 1152, v184
	v_add_u32_e32 v164, 1216, v184
	v_add_u32_e32 v165, 1280, v184
	v_add_u32_e32 v166, 1344, v184
	v_add_u32_e32 v167, 1408, v184
	v_add_u32_e32 v168, 1472, v184
	v_add_u32_e32 v169, 1536, v184
	v_add_u32_e32 v170, 1600, v184
	ds_read_u8 v162, v162
	ds_read_u8 v163, v163
	ds_read_u8 v164, v164
	ds_read_u8 v165, v165
	ds_read_u8 v166, v166
	ds_read_u8 v167, v167
	ds_read_u8 v168, v168
	ds_read_u8 v169, v169
	ds_read_u8 v170, v170
	s_waitcnt lgkmcnt(8)
	v_lshl_add_u32 v162, v162, 2, v156
	s_waitcnt lgkmcnt(7)
	v_lshl_add_u32 v163, v163, 2, v156
	s_waitcnt lgkmcnt(6)
	v_lshl_add_u32 v164, v164, 2, v156
	s_waitcnt lgkmcnt(5)
	v_lshl_add_u32 v165, v165, 2, v156
	s_waitcnt lgkmcnt(4)
	v_lshl_add_u32 v166, v166, 2, v156
	s_waitcnt lgkmcnt(3)
	v_lshl_add_u32 v167, v167, 2, v156
	s_waitcnt lgkmcnt(2)
	v_lshl_add_u32 v168, v168, 2, v156
	s_waitcnt lgkmcnt(1)
	v_lshl_add_u32 v169, v169, 2, v156
	s_waitcnt lgkmcnt(0)
	v_lshl_add_u32 v170, v170, 2, v156
	ds_read_b32 v162, v162 offset:4864
	ds_read_b32 v163, v163 offset:4864
	ds_read_b32 v164, v164 offset:4864
	ds_read_b32 v165, v165 offset:4864
	ds_read_b32 v166, v166 offset:4864
	ds_read_b32 v167, v167 offset:4864
	ds_read_b32 v168, v168 offset:4864
	ds_read_b32 v169, v169 offset:4864
	ds_read_b32 v170, v170 offset:4864
	v_lshl_add_u32 v182, v184, 2, v180
	s_waitcnt lgkmcnt(8)
	ds_write_b32 v182, v162 offset:4608
	s_waitcnt lgkmcnt(7)
	ds_write_b32 v182, v163 offset:4864
	s_waitcnt lgkmcnt(6)
	ds_write_b32 v182, v164 offset:5120
	s_waitcnt lgkmcnt(5)
	ds_write_b32 v182, v165 offset:5376
	s_waitcnt lgkmcnt(4)
	ds_write_b32 v182, v166 offset:5632
	s_waitcnt lgkmcnt(3)
	ds_write_b32 v182, v167 offset:5888
	s_waitcnt lgkmcnt(2)
	ds_write_b32 v182, v168 offset:6144
	s_waitcnt lgkmcnt(1)
	ds_write_b32 v182, v169 offset:6400
	s_waitcnt lgkmcnt(0)
	ds_write_b32 v182, v170 offset:6656
	ds_read_b32 v178, v156 offset:4988
	v_add_u32_e32 v180, 148, v180
	v_mov_b32_e32 v181, 0x7f800000
	s_waitcnt lgkmcnt(0)
; #define MFMA32(a, b, c) __builtin_amdgcn_mfma_f32_32x32x16_bf16((a), (b), (c), 0, 0, 0)
; #define NEGINF (-__builtin_inff())
; DI int crow(int i, int h) { return (i & 3) + 8 * (i >> 2) + 4 * h; }
; template <class KP, class VP, class ACT, class FILL>
; DI void attn_loop(AttnSt& st, const bf16x8 (&qf)[4], int k0, int k1, size_t vstride, KP kp, VP vp, ACT act, FILL fill) {
;     ...
;   for (int kt = k0; kt <= k1; ++kt) {
;     const int kn = (kt < k1) ? kt + 1 : k1;
;     const int kn2 = (kt + 2 <= k1) ? kt + 2 : k1;
;     {
;       const bf16_t* v0 = vp(kn);
; #pragma unroll
;       for (int j = 0; j < 8; ++j) nxt.v[j] = *(const s16x4*)(v0 + 256 * j);
;     }
;     bf16x8 k2[4];
;     {
;       const bf16_t* krow = kp(kn2);
; #pragma unroll
;       for (int ss = 0; ss < 4; ++ss) k2[ss] = *(const bf16x8*)(krow + 512 * ss);
;     }
;     f32x16 s_next;
; #pragma unroll
;     for (int i = 0; i < 16; ++i) s_next[i] = 0.f;
; #pragma unroll
;     for (int ss = 0; ss < 4; ++ss) s_next = MFMA32(nxt.k[ss], qf[ss], s_next);
; DI void moba_item(const Params& p, int b, int hd, int qb, const unsigned char* blut, const float* tbl) {
;     ...
;   attn_loop(st, qf, 0, qb, 32,
;     [&](int kt) { return K + (size_t)kt * 2048 + (h * 32 + r) * 8; },
;     [&](int kt) { return Vt + (size_t)kt * 2048 + (h * 32 + r) * 4; },
;     [&](int kt) { return __ballot((mmask >> (kt >> 3)) & 1u) != 0ull; },
;     [&](int kt, const f32x16& s, float (&lg)[16]) {
;       const bool bs = (mmask >> (kt >> 3)) & 1u;
;       if (qb * 32 - (kt * 32 + 31) >= 1513) {
;         const float b31 = tblh[31];
; #pragma unroll
;         for (int i = 0; i < 16; ++i) lg[i] = bs ? s[i] + b31 : NEGINF;
;       } else {
;         int dist[16]; float bv[16];
; #pragma unroll
;         for (int i = 0; i < 16; ++i) dist[i] = t - (kt * 32 + crow(i, h));
;         bias16(blut, tblh, dist, bv);
; #pragma unroll
;         for (int i = 0; i < 16; ++i) lg[i] = (bs && dist[i] >= 0) ? s[i] + bv[i] : NEGINF;
;       }
;     });
.Lamoba_loop:
	s_waitcnt vmcnt(2)
	s_barrier
	s_lshr_b32 s23, s56, 1
	s_add_u32 s23, s23, 2
	s_sub_u32 s61, s100, 0x4000
	s_cmp_lt_u32 s61, 0x10000
	s_cselect_b32 s61, 0x18000, s61
	s_lshr_b32 s24, s59, 1
	s_min_u32 s24, s23, s24
	s_lshl_b32 s26, s24, 13
	s_lshl_b32 s24, s58, 10
	s_add_u32 s26, s26, s24
	s_mov_b32 s27, 0
	v_lshl_add_u64 v[186:187], v[134:135], 0, s[26:27]
	v_lshl_add_u64 v[218:219], v[136:137], 0, s[26:27]
	v_add_co_u32_e32 v218, vcc, v218, v185
	v_addc_co_u32_e32 v219, vcc, 0, v219, vcc
	s_add_u32 s24, s24, s61
	s_mov_b32 m0, s24
	s_nop 0
	global_load_lds_dwordx4 v[186:187], off
	s_add_u32 s24, s24, 0x2000
	s_mov_b32 m0, s24
	s_nop 0
	global_load_lds_dwordx4 v[218:219], off
	s_cmp_le_u32 s56, s60
	s_cbranch_scc0 .Lamoba_skip
	v_lshl_add_u32 v186, v185, 1, s100
	ds_read_b128 v[96:99], v186 offset:0
	ds_read_b128 v[100:103], v186 offset:1024
	ds_read_b128 v[104:107], v186 offset:2048
	ds_read_b128 v[108:111], v186 offset:3072
	ds_read_b128 v[112:115], v186 offset:4096
	ds_read_b128 v[116:119], v186 offset:5120
	ds_read_b128 v[120:123], v186 offset:6144
	ds_read_b128 v[124:127], v186 offset:7168
	s_sub_i32 s61, s60, s56
	s_lshr_b32 s23, s56, 3
	v_bfe_u32 v184, v157, s23, 1
	v_cmp_eq_u32_e64 s[62:63], 1, v184
	s_waitcnt lgkmcnt(0)
	v_mfma_f32_32x32x16_bf16 v[32:47], v[96:99], v[80:83], 0
	v_mfma_f32_32x32x16_bf16 v[48:63], v[112:115], v[80:83], 0
	v_mfma_f32_32x32x16_bf16 v[32:47], v[100:103], v[84:87], v[32:47]
	v_mfma_f32_32x32x16_bf16 v[48:63], v[116:119], v[84:87], v[48:63]
	v_mfma_f32_32x32x16_bf16 v[32:47], v[104:107], v[88:91], v[32:47]
	v_mfma_f32_32x32x16_bf16 v[48:63], v[120:123], v[88:91], v[48:63]
	v_mfma_f32_32x32x16_bf16 v[32:47], v[108:111], v[92:95], v[32:47]
	v_mfma_f32_32x32x16_bf16 v[48:63], v[124:127], v[92:95], v[48:63]
	v_add_u32_e32 v218, s100, v185
	ds_read_b64 v[64:65], v218 offset:8192
	ds_read_b64 v[66:67], v218 offset:8704
	ds_read_b64 v[68:69], v218 offset:9216
	ds_read_b64 v[70:71], v218 offset:9728
	ds_read_b64 v[72:73], v218 offset:10240
	ds_read_b64 v[74:75], v218 offset:10752
	ds_read_b64 v[76:77], v218 offset:11264
	ds_read_b64 v[78:79], v218 offset:11776
	ds_read_b64 v[138:139], v218 offset:12288
	ds_read_b64 v[140:141], v218 offset:12800
	ds_read_b64 v[142:143], v218 offset:13312
	ds_read_b64 v[144:145], v218 offset:13824
	ds_read_b64 v[146:147], v218 offset:14336
	ds_read_b64 v[148:149], v218 offset:14848
	ds_read_b64 v[150:151], v218 offset:15360
	ds_read_b64 v[152:153], v218 offset:15872
	s_cmp_ge_i32 s61, 50
	s_cbranch_scc1 .Lamoba_far
	s_lshl_b32 s23, s61, 5
	v_add_u32_e32 v179, s23, v158
	v_lshl_add_u32 v182, v179, 2, v180
	v_subrev_u32_e32 v183, 128, v182
	ds_read_b32 v162, v182 offset:108
	ds_read_b32 v163, v182 offset:104
	ds_read_b32 v164, v182 offset:100
	ds_read_b32 v165, v182 offset:96
	ds_read_b32 v166, v182 offset:76
	ds_read_b32 v167, v182 offset:72
	ds_read_b32 v168, v182 offset:68
	ds_read_b32 v169, v182 offset:64
	ds_read_b32 v170, v182 offset:44
	ds_read_b32 v171, v182 offset:40
	ds_read_b32 v172, v182 offset:36
	ds_read_b32 v173, v182 offset:32
	ds_read_b32 v174, v182 offset:12
	ds_read_b32 v175, v182 offset:8
	ds_read_b32 v176, v182 offset:4
	ds_read_b32 v177, v182 offset:0
	s_waitcnt lgkmcnt(8)
	v_add_f32_e32 v32, v32, v162
	v_add_f32_e32 v33, v33, v163
	v_add_f32_e32 v34, v34, v164
	v_add_f32_e32 v35, v35, v165
	v_add_f32_e32 v36, v36, v166
	v_add_f32_e32 v37, v37, v167
	v_add_f32_e32 v38, v38, v168
	v_add_f32_e32 v39, v39, v169
	s_waitcnt lgkmcnt(0)
	v_add_f32_e32 v40, v40, v170
	v_add_f32_e32 v41, v41, v171
	v_add_f32_e32 v42, v42, v172
	v_add_f32_e32 v43, v43, v173
	v_add_f32_e32 v44, v44, v174
	v_add_f32_e32 v45, v45, v175
	v_add_f32_e32 v46, v46, v176
	v_add_f32_e32 v47, v47, v177
	ds_read_b32 v162, v183 offset:108
	ds_read_b32 v163, v183 offset:104
	ds_read_b32 v164, v183 offset:100
	ds_read_b32 v165, v183 offset:96
	ds_read_b32 v166, v183 offset:76
	ds_read_b32 v167, v183 offset:72
	ds_read_b32 v168, v183 offset:68
	ds_read_b32 v169, v183 offset:64
	ds_read_b32 v170, v183 offset:44
	ds_read_b32 v171, v183 offset:40
	ds_read_b32 v172, v183 offset:36
	ds_read_b32 v173, v183 offset:32
	ds_read_b32 v174, v183 offset:12
	ds_read_b32 v175, v183 offset:8
	ds_read_b32 v176, v183 offset:4
	ds_read_b32 v177, v183 offset:0
	s_waitcnt lgkmcnt(8)
	v_add_f32_e32 v48, v48, v162
	v_add_f32_e32 v49, v49, v163
	v_add_f32_e32 v50, v50, v164
	v_add_f32_e32 v51, v51, v165
	v_add_f32_e32 v52, v52, v166
	v_add_f32_e32 v53, v53, v167
	v_add_f32_e32 v54, v54, v168
	v_add_f32_e32 v55, v55, v169
	s_waitcnt lgkmcnt(0)
	v_add_f32_e32 v56, v56, v170
	v_add_f32_e32 v57, v57, v171
	v_add_f32_e32 v58, v58, v172
	v_add_f32_e32 v59, v59, v173
	v_add_f32_e32 v60, v60, v174
	v_add_f32_e32 v61, v61, v175
	v_add_f32_e32 v62, v62, v176
	v_add_f32_e32 v63, v63, v177
	s_cmp_ge_i32 s61, 2
	s_cbranch_scc1 .Lamoba_softmax
; #define NEGINF (-__builtin_inff())
; DI int crow(int i, int h) { return (i & 3) + 8 * (i >> 2) + 4 * h; }
; DI void moba_item(const Params& p, int b, int hd, int qb, const unsigned char* blut, const float* tbl) {
;     ...
;         int dist[16]; float bv[16];
; #pragma unroll
;         for (int i = 0; i < 16; ++i) dist[i] = t - (kt * 32 + crow(i, h));
;         bias16(blut, tblh, dist, bv);
; #pragma unroll
;         for (int i = 0; i < 16; ++i) lg[i] = (bs && dist[i] >= 0) ? s[i] + bv[i] : NEGINF;
	v_subrev_u32_e32 v184, 32, v179
	v_cmp_le_i32_e32 vcc, 0, v179
	s_nop 1
	v_cndmask_b32_e32 v32, v199, v32, vcc
	v_cmp_le_i32_e32 vcc, 1, v179
	s_nop 1
	v_cndmask_b32_e32 v33, v199, v33, vcc
	v_cmp_le_i32_e32 vcc, 2, v179
	s_nop 1
	v_cndmask_b32_e32 v34, v199, v34, vcc
	v_cmp_le_i32_e32 vcc, 3, v179
	s_nop 1
	v_cndmask_b32_e32 v35, v199, v35, vcc
	v_cmp_le_i32_e32 vcc, 8, v179
	s_nop 1
	v_cndmask_b32_e32 v36, v199, v36, vcc
	v_cmp_le_i32_e32 vcc, 9, v179
	s_nop 1
	v_cndmask_b32_e32 v37, v199, v37, vcc
	v_cmp_le_i32_e32 vcc, 10, v179
	s_nop 1
	v_cndmask_b32_e32 v38, v199, v38, vcc
	v_cmp_le_i32_e32 vcc, 11, v179
	s_nop 1
	v_cndmask_b32_e32 v39, v199, v39, vcc
	v_cmp_le_i32_e32 vcc, 16, v179
	s_nop 1
	v_cndmask_b32_e32 v40, v199, v40, vcc
	v_cmp_le_i32_e32 vcc, 17, v179
	s_nop 1
	v_cndmask_b32_e32 v41, v199, v41, vcc
	v_cmp_le_i32_e32 vcc, 18, v179
	s_nop 1
	v_cndmask_b32_e32 v42, v199, v42, vcc
	v_cmp_le_i32_e32 vcc, 19, v179
	s_nop 1
	v_cndmask_b32_e32 v43, v199, v43, vcc
	v_cmp_le_i32_e32 vcc, 24, v179
	s_nop 1
	v_cndmask_b32_e32 v44, v199, v44, vcc
	v_cmp_le_i32_e32 vcc, 25, v179
	s_nop 1
	v_cndmask_b32_e32 v45, v199, v45, vcc
	v_cmp_le_i32_e32 vcc, 26, v179
	s_nop 1
	v_cndmask_b32_e32 v46, v199, v46, vcc
	v_cmp_le_i32_e32 vcc, 27, v179
	s_nop 1
	v_cndmask_b32_e32 v47, v199, v47, vcc
	v_cmp_le_i32_e32 vcc, 0, v184
	s_nop 1
	v_cndmask_b32_e32 v48, v199, v48, vcc
	v_cmp_le_i32_e32 vcc, 1, v184
	s_nop 1
	v_cndmask_b32_e32 v49, v199, v49, vcc
	v_cmp_le_i32_e32 vcc, 2, v184
	s_nop 1
	v_cndmask_b32_e32 v50, v199, v50, vcc
	v_cmp_le_i32_e32 vcc, 3, v184
	s_nop 1
	v_cndmask_b32_e32 v51, v199, v51, vcc
	v_cmp_le_i32_e32 vcc, 8, v184
	s_nop 1
	v_cndmask_b32_e32 v52, v199, v52, vcc
	v_cmp_le_i32_e32 vcc, 9, v184
	s_nop 1
	v_cndmask_b32_e32 v53, v199, v53, vcc
	v_cmp_le_i32_e32 vcc, 10, v184
	s_nop 1
	v_cndmask_b32_e32 v54, v199, v54, vcc
	v_cmp_le_i32_e32 vcc, 11, v184
	s_nop 1
	v_cndmask_b32_e32 v55, v199, v55, vcc
	v_cmp_le_i32_e32 vcc, 16, v184
	s_nop 1
	v_cndmask_b32_e32 v56, v199, v56, vcc
	v_cmp_le_i32_e32 vcc, 17, v184
	s_nop 1
	v_cndmask_b32_e32 v57, v199, v57, vcc
	v_cmp_le_i32_e32 vcc, 18, v184
	s_nop 1
	v_cndmask_b32_e32 v58, v199, v58, vcc
	v_cmp_le_i32_e32 vcc, 19, v184
	s_nop 1
	v_cndmask_b32_e32 v59, v199, v59, vcc
	v_cmp_le_i32_e32 vcc, 24, v184
	s_nop 1
	v_cndmask_b32_e32 v60, v199, v60, vcc
	v_cmp_le_i32_e32 vcc, 25, v184
	s_nop 1
	v_cndmask_b32_e32 v61, v199, v61, vcc
	v_cmp_le_i32_e32 vcc, 26, v184
	s_nop 1
	v_cndmask_b32_e32 v62, v199, v62, vcc
	v_cmp_le_i32_e32 vcc, 27, v184
	s_nop 1
	v_cndmask_b32_e32 v63, v199, v63, vcc
	s_branch .Lamoba_softmax

; #define MFMA32(a, b, c) __builtin_amdgcn_mfma_f32_32x32x16_bf16((a), (b), (c), 0, 0, 0)
; DI unsigned pack2(float a, float b) { unsigned r; asm("v_cvt_pk_bf16_f32 %0, %1, %2" : "=v"(r) : "v"(a), "v"(b)); return r; }
; DI void softmax_step_r(AttnSt& st, const float (&lg)[16], const KVT& t) {
;     ...
; #pragma unroll
;   for (int s2 = 0; s2 < 2; ++s2) {
;     u32x4 pk; pk.x = pack2(pr[8 * s2], pr[8 * s2 + 1]); pk.y = pack2(pr[8 * s2 + 2], pr[8 * s2 + 3]); pk.z = pack2(pr[8 * s2 + 4], pr[8 * s2 + 5]); pk.w = pack2(pr[8 * s2 + 6], pr[8 * s2 + 7]);
;     const bf16x8 pb = __builtin_bit_cast(bf16x8, pk);
;     const bf16x8 va0 = __builtin_shufflevector(t.v[s2 * 4 + 0], t.v[s2 * 4 + 1], 0, 1, 2, 3, 4, 5, 6, 7);
;     st.o0 = MFMA32(va0, pb, st.o0);
;     const bf16x8 va1 = __builtin_shufflevector(t.v[s2 * 4 + 2], t.v[s2 * 4 + 3], 0, 1, 2, 3, 4, 5, 6, 7);
;     st.o1 = MFMA32(va1, pb, st.o1);
;   }
; template <class KP, class VP, class ACT, class FILL>
; DI void attn_loop(AttnSt& st, const bf16x8 (&qf)[4], int k0, int k1, size_t vstride, KP kp, VP vp, ACT act, FILL fill) {
;     ...
;   for (int kt = k0; kt <= k1; ++kt) {
;     const int kn = (kt < k1) ? kt + 1 : k1;
;     const int kn2 = (kt + 2 <= k1) ? kt + 2 : k1;
;     {
;       const bf16_t* v0 = vp(kn);
; #pragma unroll
;       for (int j = 0; j < 8; ++j) nxt.v[j] = *(const s16x4*)(v0 + 256 * j);
;     }
;     bf16x8 k2[4];
;     {
;       const bf16_t* krow = kp(kn2);
; #pragma unroll
;       for (int ss = 0; ss < 4; ++ss) k2[ss] = *(const bf16x8*)(krow + 512 * ss);
;     }
;     f32x16 s_next;
; #pragma unroll
;     for (int i = 0; i < 16; ++i) s_next[i] = 0.f;
; #pragma unroll
;     for (int ss = 0; ss < 4; ++ss) s_next = MFMA32(nxt.k[ss], qf[ss], s_next);
;     if (act(kt)) {
;       float lg[16];
;       fill(kt, s_cur, lg);
;       softmax_step_r(st, lg, cur);
;     }
;     s_cur = s_next;
; #pragma unroll
;     for (int i = 0; i < 8; ++i) cur.v[i] = nxt.v[i];
; #pragma unroll
;     for (int ss = 0; ss < 4; ++ss) nxt.k[ss] = k2[ss];
;   }
.Lamoba_noscale:
	v_cvt_pk_bf16_f32 v162, v32, v33
	v_cvt_pk_bf16_f32 v163, v34, v35
	v_cvt_pk_bf16_f32 v164, v36, v37
	v_cvt_pk_bf16_f32 v165, v38, v39
	v_cvt_pk_bf16_f32 v166, v40, v41
	v_cvt_pk_bf16_f32 v167, v42, v43
	v_cvt_pk_bf16_f32 v168, v44, v45
	v_cvt_pk_bf16_f32 v169, v46, v47
	v_cvt_pk_bf16_f32 v170, v48, v49
	v_cvt_pk_bf16_f32 v171, v50, v51
	v_cvt_pk_bf16_f32 v172, v52, v53
	v_cvt_pk_bf16_f32 v173, v54, v55
	v_cvt_pk_bf16_f32 v174, v56, v57
	v_cvt_pk_bf16_f32 v175, v58, v59
	v_cvt_pk_bf16_f32 v176, v60, v61
	v_cvt_pk_bf16_f32 v177, v62, v63
	s_waitcnt lgkmcnt(0)
	s_nop 1
	v_mfma_f32_32x32x16_bf16 v[0:15], v[64:67], v[162:165], v[0:15]
	v_mfma_f32_32x32x16_bf16 v[16:31], v[68:71], v[162:165], v[16:31]
	v_mfma_f32_32x32x16_bf16 v[0:15], v[72:75], v[166:169], v[0:15]
	v_mfma_f32_32x32x16_bf16 v[16:31], v[76:79], v[166:169], v[16:31]
	v_mfma_f32_32x32x16_bf16 v[0:15], v[138:141], v[170:173], v[0:15]
	v_mfma_f32_32x32x16_bf16 v[16:31], v[142:145], v[170:173], v[16:31]
	v_mfma_f32_32x32x16_bf16 v[0:15], v[146:149], v[174:177], v[0:15]
	v_mfma_f32_32x32x16_bf16 v[16:31], v[150:153], v[174:177], v[16:31]
.Lamoba_skip:
	s_add_u32 s100, s100, 0x4000
	s_cmp_eq_u32 s100, 0x1c000
	s_cselect_b32 s100, 0x10000, s100
	s_add_u32 s56, s56, 2
	s_cmp_le_u32 s56, s59
	s_cbranch_scc1 .Lamoba_loop
	s_nop 15
	s_waitcnt vmcnt(0)
	s_mov_b64 s[58:59], 0
	s_branch .LBB0_933
.LBB0_955:
	s_or_b64 exec, exec, s[14:15]
	s_barrier
	s_mov_b64 s[8:9], 0
